# static s_setprio 1 for waves 0-3 across the P2 mixer phase (the other half of the per-half A/B)
# speedup vs baseline: 1.0115x; 1.0115x over previous
; #define MKCTX() Ctx C; size_t z_ = 0; { int t_ = threadIdx.x; asm volatile("" : "+s"(z_), "+v"(t_)); unsigned char* ws_ = p.ws + z_; const float* rb_ = p.in[1] + z_; \
;     C.lds = (LAS unsigned char*)lds_raw + 64; C.tid = t_; C.lane = t_ & 63; C.wave = __builtin_amdgcn_readfirstlane(t_ >> 6); C.relb = rb_; C.ws = ws_; }
; __global__ void __launch_bounds__(512) hybrid_fwd(Params p) {
;     ...
;         for (;;) {
;             MKCTX();
;             unsigned* ctl = (unsigned*)(C.ws + WS_CTL);
;             __syncthreads();
;             if (C.tid == 0) s_unit = (int)atomicAdd(ctl + 64 * (1 + l), 1u);
;             __syncthreads();
;             const int u = s_unit;
.LBB0_317:
	s_mov_b64 s[20:21], 0
	v_mov_b32_e32 v132, v229
	s_add_u32 s64, s92, s20
	s_addc_u32 s65, s93, s21
	v_readfirstlane_b32 s73, v132
	s_cmp_ge_u32 s73, 0x100
	s_cbranch_scc1 .Lprio_skip
	s_setprio 1
